# phase-10 (w1 layer0) GEMM epilogue rewritten: dpp pair-packed dword stores, saddr addressing
# baseline (speedup 1.0000x reference)
; __device__ __forceinline__ bf16_t f2bf(float x) { return (bf16_t)(cvtpk(x, 0.f) & 0xffffu); }
; __device__ __forceinline__ int crow(int r, int hi) { return (r & 3) + 8 * (r >> 2) + 4 * hi; }
; template <class Epi>
; __device__ __forceinline__ void gemm8p(const bf16_t* __restrict__ A, int lda, const bf16_t* __restrict__ Bt, int ldb, int K,
;                                        LP lds, const Epi& epi, bool pre = false, const bf16_t* An = nullptr, const bf16_t* Bn = nullptr) {
;     ...
;   int e_rr = wr * 64, e_cc = wc * 32 + r32, e_hi = hi;
;   asm volatile("" : "+v"(e_rr), "+v"(e_cc), "+v"(e_hi));
; #pragma unroll
;   for (int a = 0; a < 2; ++a)
; #pragma unroll
;     for (int b = 0; b < 2; ++b)
; #pragma unroll
;       for (int m = 0; m < 2; ++m) { __builtin_amdgcn_sched_barrier(0); epi(a * 128 + e_rr + m * 32, b * 128 + e_cc, e_hi, acc[a][b][m]); }
; __device__ __forceinline__ void phase_gemm_w1(const Params& p, const bf16_t* __restrict__ WT, bool xonly, LP lds) {
;     ...
;     gemm8p(H + (size_t)row0 * 1024, 1024, WT + (size_t)col0 * 1024, 1024, 1024, lds, [&](int rr, int cc, int hi, f32x16 v) __attribute__((always_inline)) {
;       const int col = col0 + cc;
; #pragma unroll
;       for (int r = 0; r < 16; ++r) { const size_t row = row0 + rr + crow(r, hi); const float a = fmaxf(v[r], 0.f); __builtin_nontemporal_store(f2bf(a * a), U + row * 4096 + col); }
;     }, pre, hasn ? H + (size_t)rown * 1024 : nullptr, hasn ? WT + (size_t)coln * 1024 : nullptr);
.LBB0_1744:
	s_nop 0
	s_lshl_b32 s100, s60, 13
	s_lshl_b32 s101, s2, 9
	s_add_u32 s100, s100, s101
	s_add_u32 s98, s6, s100
	s_addc_u32 s99, s7, 0
	v_lshl_add_u32 v130, v150, 2, v149
	v_and_b32_e32 v131, 1, v151
	v_add_u32_e32 v130, v130, v131
	v_sub_u32_e32 v132, v151, v131
	v_mul_u32_u24_e32 v130, 0x2000, v130
	v_lshl_add_u32 v130, v132, 1, v130
	v_sub_u32_e32 v132, 0, v131
	v_and_b32_e32 v132, 0x6060606, v132
	v_xor_b32_e32 v131, 0x5040100, v132
	v_max_f32_e32 v112, 0, v112
	v_max_f32_e32 v113, 0, v113
	v_max_f32_e32 v80, 0, v80
	v_max_f32_e32 v81, 0, v81
	v_pk_mul_f32 v[112:113], v[112:113], v[112:113]
	v_pk_mul_f32 v[80:81], v[80:81], v[80:81]
	v_cvt_pk_bf16_f32 v133, v112, v113
	v_cvt_pk_bf16_f32 v134, v80, v81
	s_nop 1
	v_mov_b32_dpp v135, v133 quad_perm:[1,0,3,2] row_mask:0xf bank_mask:0xf
	v_mov_b32_dpp v136, v134 quad_perm:[1,0,3,2] row_mask:0xf bank_mask:0xf
	v_perm_b32 v137, v135, v133, v131
	v_perm_b32 v138, v136, v134, v131
	global_store_dword v130, v137, s[98:99] nt
	global_store_dword v130, v138, s[98:99] offset:256 nt
	v_max_f32_e32 v114, 0, v114
	v_max_f32_e32 v115, 0, v115
	v_max_f32_e32 v82, 0, v82
	v_max_f32_e32 v83, 0, v83
	v_pk_mul_f32 v[114:115], v[114:115], v[114:115]
	v_pk_mul_f32 v[82:83], v[82:83], v[82:83]
	v_cvt_pk_bf16_f32 v139, v114, v115
	v_cvt_pk_bf16_f32 v140, v82, v83
	s_add_u32 s98, s98, 0x4000
	s_addc_u32 s99, s99, 0
	v_mov_b32_dpp v141, v139 quad_perm:[1,0,3,2] row_mask:0xf bank_mask:0xf
	v_mov_b32_dpp v142, v140 quad_perm:[1,0,3,2] row_mask:0xf bank_mask:0xf
	v_perm_b32 v143, v141, v139, v131
	v_perm_b32 v144, v142, v140, v131
	global_store_dword v130, v143, s[98:99] nt
	global_store_dword v130, v144, s[98:99] offset:256 nt
	v_max_f32_e32 v116, 0, v116
	v_max_f32_e32 v117, 0, v117
	v_max_f32_e32 v84, 0, v84
	v_max_f32_e32 v85, 0, v85
	v_pk_mul_f32 v[116:117], v[116:117], v[116:117]
	v_pk_mul_f32 v[84:85], v[84:85], v[84:85]
	v_cvt_pk_bf16_f32 v133, v116, v117
	v_cvt_pk_bf16_f32 v134, v84, v85
	s_add_u32 s98, s98, 0xc000
	s_addc_u32 s99, s99, 0
	v_mov_b32_dpp v135, v133 quad_perm:[1,0,3,2] row_mask:0xf bank_mask:0xf
	v_mov_b32_dpp v136, v134 quad_perm:[1,0,3,2] row_mask:0xf bank_mask:0xf
	v_perm_b32 v137, v135, v133, v131
	v_perm_b32 v138, v136, v134, v131
	global_store_dword v130, v137, s[98:99] nt
	global_store_dword v130, v138, s[98:99] offset:256 nt
	v_max_f32_e32 v118, 0, v118
	v_max_f32_e32 v119, 0, v119
	v_max_f32_e32 v86, 0, v86
	v_max_f32_e32 v87, 0, v87
	v_pk_mul_f32 v[118:119], v[118:119], v[118:119]
	v_pk_mul_f32 v[86:87], v[86:87], v[86:87]
	v_cvt_pk_bf16_f32 v139, v118, v119
	v_cvt_pk_bf16_f32 v140, v86, v87
	s_add_u32 s98, s98, 0x4000
	s_addc_u32 s99, s99, 0
	v_mov_b32_dpp v141, v139 quad_perm:[1,0,3,2] row_mask:0xf bank_mask:0xf
	v_mov_b32_dpp v142, v140 quad_perm:[1,0,3,2] row_mask:0xf bank_mask:0xf
	v_perm_b32 v143, v141, v139, v131
	v_perm_b32 v144, v142, v140, v131
	global_store_dword v130, v143, s[98:99] nt
	global_store_dword v130, v144, s[98:99] offset:256 nt
	v_max_f32_e32 v120, 0, v120
	v_max_f32_e32 v121, 0, v121
	v_max_f32_e32 v88, 0, v88
	v_max_f32_e32 v89, 0, v89
	v_pk_mul_f32 v[120:121], v[120:121], v[120:121]
	v_pk_mul_f32 v[88:89], v[88:89], v[88:89]
	v_cvt_pk_bf16_f32 v133, v120, v121
	v_cvt_pk_bf16_f32 v134, v88, v89
	s_add_u32 s98, s98, 0xc000
	s_addc_u32 s99, s99, 0
	v_mov_b32_dpp v135, v133 quad_perm:[1,0,3,2] row_mask:0xf bank_mask:0xf
	v_mov_b32_dpp v136, v134 quad_perm:[1,0,3,2] row_mask:0xf bank_mask:0xf
	v_perm_b32 v137, v135, v133, v131
	v_perm_b32 v138, v136, v134, v131
	global_store_dword v130, v137, s[98:99] nt
	global_store_dword v130, v138, s[98:99] offset:256 nt
	v_max_f32_e32 v122, 0, v122
	v_max_f32_e32 v123, 0, v123
	v_max_f32_e32 v90, 0, v90
	v_max_f32_e32 v91, 0, v91
	v_pk_mul_f32 v[122:123], v[122:123], v[122:123]
	v_pk_mul_f32 v[90:91], v[90:91], v[90:91]
	v_cvt_pk_bf16_f32 v139, v122, v123
	v_cvt_pk_bf16_f32 v140, v90, v91
	s_add_u32 s98, s98, 0x4000
	s_addc_u32 s99, s99, 0
	v_mov_b32_dpp v141, v139 quad_perm:[1,0,3,2] row_mask:0xf bank_mask:0xf
	v_mov_b32_dpp v142, v140 quad_perm:[1,0,3,2] row_mask:0xf bank_mask:0xf
	v_perm_b32 v143, v141, v139, v131
	v_perm_b32 v144, v142, v140, v131
	global_store_dword v130, v143, s[98:99] nt
	global_store_dword v130, v144, s[98:99] offset:256 nt
	v_max_f32_e32 v124, 0, v124
	v_max_f32_e32 v125, 0, v125
	v_max_f32_e32 v92, 0, v92
	v_max_f32_e32 v93, 0, v93
	v_pk_mul_f32 v[124:125], v[124:125], v[124:125]
	v_pk_mul_f32 v[92:93], v[92:93], v[92:93]
	v_cvt_pk_bf16_f32 v133, v124, v125
	v_cvt_pk_bf16_f32 v134, v92, v93
	s_add_u32 s98, s98, 0xc000
	s_addc_u32 s99, s99, 0
	v_mov_b32_dpp v135, v133 quad_perm:[1,0,3,2] row_mask:0xf bank_mask:0xf
	v_mov_b32_dpp v136, v134 quad_perm:[1,0,3,2] row_mask:0xf bank_mask:0xf
	v_perm_b32 v137, v135, v133, v131
	v_perm_b32 v138, v136, v134, v131
	global_store_dword v130, v137, s[98:99] nt
	global_store_dword v130, v138, s[98:99] offset:256 nt
	v_max_f32_e32 v126, 0, v126
	v_max_f32_e32 v127, 0, v127
	v_max_f32_e32 v94, 0, v94
	v_max_f32_e32 v95, 0, v95
	v_pk_mul_f32 v[126:127], v[126:127], v[126:127]
	v_pk_mul_f32 v[94:95], v[94:95], v[94:95]
	v_cvt_pk_bf16_f32 v139, v126, v127
	v_cvt_pk_bf16_f32 v140, v94, v95
	s_add_u32 s98, s98, 0x4000
	s_addc_u32 s99, s99, 0
	v_mov_b32_dpp v141, v139 quad_perm:[1,0,3,2] row_mask:0xf bank_mask:0xf
	v_mov_b32_dpp v142, v140 quad_perm:[1,0,3,2] row_mask:0xf bank_mask:0xf
	v_perm_b32 v143, v141, v139, v131
	v_perm_b32 v144, v142, v140, v131
	global_store_dword v130, v143, s[98:99] nt
	global_store_dword v130, v144, s[98:99] offset:256 nt
	v_max_f32_e32 v96, 0, v96
	v_max_f32_e32 v97, 0, v97
	v_max_f32_e32 v64, 0, v64
	v_max_f32_e32 v65, 0, v65
; __device__ __forceinline__ bf16_t f2bf(float x) { return (bf16_t)(cvtpk(x, 0.f) & 0xffffu); }
; __device__ __forceinline__ int crow(int r, int hi) { return (r & 3) + 8 * (r >> 2) + 4 * hi; }
; template <class Epi>
; __device__ __forceinline__ void gemm8p(const bf16_t* __restrict__ A, int lda, const bf16_t* __restrict__ Bt, int ldb, int K,
;                                        LP lds, const Epi& epi, bool pre = false, const bf16_t* An = nullptr, const bf16_t* Bn = nullptr) {
;     ...
;   int e_rr = wr * 64, e_cc = wc * 32 + r32, e_hi = hi;
;   asm volatile("" : "+v"(e_rr), "+v"(e_cc), "+v"(e_hi));
; #pragma unroll
;   for (int a = 0; a < 2; ++a)
; #pragma unroll
;     for (int b = 0; b < 2; ++b)
; #pragma unroll
;       for (int m = 0; m < 2; ++m) { __builtin_amdgcn_sched_barrier(0); epi(a * 128 + e_rr + m * 32, b * 128 + e_cc, e_hi, acc[a][b][m]); }
; __device__ __forceinline__ void phase_gemm_w1(const Params& p, const bf16_t* __restrict__ WT, bool xonly, LP lds) {
;     ...
;     gemm8p(H + (size_t)row0 * 1024, 1024, WT + (size_t)col0 * 1024, 1024, 1024, lds, [&](int rr, int cc, int hi, f32x16 v) __attribute__((always_inline)) {
;       const int col = col0 + cc;
; #pragma unroll
;       for (int r = 0; r < 16; ++r) { const size_t row = row0 + rr + crow(r, hi); const float a = fmaxf(v[r], 0.f); __builtin_nontemporal_store(f2bf(a * a), U + row * 4096 + col); }
;     }, pre, hasn ? H + (size_t)rown * 1024 : nullptr, hasn ? WT + (size_t)coln * 1024 : nullptr);
	v_pk_mul_f32 v[96:97], v[96:97], v[96:97]
	v_pk_mul_f32 v[64:65], v[64:65], v[64:65]
	v_cvt_pk_bf16_f32 v133, v96, v97
	v_cvt_pk_bf16_f32 v134, v64, v65
	s_add_u32 s98, s98, 0xc000
	s_addc_u32 s99, s99, 0
	v_mov_b32_dpp v135, v133 quad_perm:[1,0,3,2] row_mask:0xf bank_mask:0xf
	v_mov_b32_dpp v136, v134 quad_perm:[1,0,3,2] row_mask:0xf bank_mask:0xf
	v_perm_b32 v137, v135, v133, v131
	v_perm_b32 v138, v136, v134, v131
	global_store_dword v130, v137, s[98:99] nt
	global_store_dword v130, v138, s[98:99] offset:256 nt
	v_max_f32_e32 v98, 0, v98
	v_max_f32_e32 v99, 0, v99
	v_max_f32_e32 v66, 0, v66
	v_max_f32_e32 v67, 0, v67
	v_pk_mul_f32 v[98:99], v[98:99], v[98:99]
	v_pk_mul_f32 v[66:67], v[66:67], v[66:67]
	v_cvt_pk_bf16_f32 v139, v98, v99
	v_cvt_pk_bf16_f32 v140, v66, v67
	s_add_u32 s98, s98, 0x4000
	s_addc_u32 s99, s99, 0
	v_mov_b32_dpp v141, v139 quad_perm:[1,0,3,2] row_mask:0xf bank_mask:0xf
	v_mov_b32_dpp v142, v140 quad_perm:[1,0,3,2] row_mask:0xf bank_mask:0xf
	v_perm_b32 v143, v141, v139, v131
	v_perm_b32 v144, v142, v140, v131
	global_store_dword v130, v143, s[98:99] nt
	global_store_dword v130, v144, s[98:99] offset:256 nt
	v_max_f32_e32 v100, 0, v100
	v_max_f32_e32 v101, 0, v101
	v_max_f32_e32 v68, 0, v68
	v_max_f32_e32 v69, 0, v69
	v_pk_mul_f32 v[100:101], v[100:101], v[100:101]
	v_pk_mul_f32 v[68:69], v[68:69], v[68:69]
	v_cvt_pk_bf16_f32 v133, v100, v101
	v_cvt_pk_bf16_f32 v134, v68, v69
	s_add_u32 s98, s98, 0xc000
	s_addc_u32 s99, s99, 0
	v_mov_b32_dpp v135, v133 quad_perm:[1,0,3,2] row_mask:0xf bank_mask:0xf
	v_mov_b32_dpp v136, v134 quad_perm:[1,0,3,2] row_mask:0xf bank_mask:0xf
	v_perm_b32 v137, v135, v133, v131
	v_perm_b32 v138, v136, v134, v131
	global_store_dword v130, v137, s[98:99] nt
	global_store_dword v130, v138, s[98:99] offset:256 nt
	v_max_f32_e32 v102, 0, v102
	v_max_f32_e32 v103, 0, v103
	v_max_f32_e32 v70, 0, v70
	v_max_f32_e32 v71, 0, v71
	v_pk_mul_f32 v[102:103], v[102:103], v[102:103]
	v_pk_mul_f32 v[70:71], v[70:71], v[70:71]
	v_cvt_pk_bf16_f32 v139, v102, v103
	v_cvt_pk_bf16_f32 v140, v70, v71
	s_add_u32 s98, s98, 0x4000
	s_addc_u32 s99, s99, 0
	v_mov_b32_dpp v141, v139 quad_perm:[1,0,3,2] row_mask:0xf bank_mask:0xf
	v_mov_b32_dpp v142, v140 quad_perm:[1,0,3,2] row_mask:0xf bank_mask:0xf
	v_perm_b32 v143, v141, v139, v131
	v_perm_b32 v144, v142, v140, v131
	global_store_dword v130, v143, s[98:99] nt
	global_store_dword v130, v144, s[98:99] offset:256 nt
	v_max_f32_e32 v104, 0, v104
	v_max_f32_e32 v105, 0, v105
	v_max_f32_e32 v72, 0, v72
	v_max_f32_e32 v73, 0, v73
	v_pk_mul_f32 v[104:105], v[104:105], v[104:105]
	v_pk_mul_f32 v[72:73], v[72:73], v[72:73]
	v_cvt_pk_bf16_f32 v133, v104, v105
	v_cvt_pk_bf16_f32 v134, v72, v73
	s_add_u32 s98, s98, 0xc000
	s_addc_u32 s99, s99, 0
	v_mov_b32_dpp v135, v133 quad_perm:[1,0,3,2] row_mask:0xf bank_mask:0xf
	v_mov_b32_dpp v136, v134 quad_perm:[1,0,3,2] row_mask:0xf bank_mask:0xf
	v_perm_b32 v137, v135, v133, v131
	v_perm_b32 v138, v136, v134, v131
	global_store_dword v130, v137, s[98:99] nt
	global_store_dword v130, v138, s[98:99] offset:256 nt
	v_max_f32_e32 v106, 0, v106
	v_max_f32_e32 v107, 0, v107
	v_max_f32_e32 v74, 0, v74
	v_max_f32_e32 v75, 0, v75
	v_pk_mul_f32 v[106:107], v[106:107], v[106:107]
	v_pk_mul_f32 v[74:75], v[74:75], v[74:75]
	v_cvt_pk_bf16_f32 v139, v106, v107
	v_cvt_pk_bf16_f32 v140, v74, v75
	s_add_u32 s98, s98, 0x4000
	s_addc_u32 s99, s99, 0
	v_mov_b32_dpp v141, v139 quad_perm:[1,0,3,2] row_mask:0xf bank_mask:0xf
	v_mov_b32_dpp v142, v140 quad_perm:[1,0,3,2] row_mask:0xf bank_mask:0xf
	v_perm_b32 v143, v141, v139, v131
	v_perm_b32 v144, v142, v140, v131
	global_store_dword v130, v143, s[98:99] nt
	global_store_dword v130, v144, s[98:99] offset:256 nt
	v_max_f32_e32 v108, 0, v108
	v_max_f32_e32 v109, 0, v109
	v_max_f32_e32 v76, 0, v76
	v_max_f32_e32 v77, 0, v77
	v_pk_mul_f32 v[108:109], v[108:109], v[108:109]
	v_pk_mul_f32 v[76:77], v[76:77], v[76:77]
	v_cvt_pk_bf16_f32 v133, v108, v109
	v_cvt_pk_bf16_f32 v134, v76, v77
	s_add_u32 s98, s98, 0xc000
	s_addc_u32 s99, s99, 0
	v_mov_b32_dpp v135, v133 quad_perm:[1,0,3,2] row_mask:0xf bank_mask:0xf
	v_mov_b32_dpp v136, v134 quad_perm:[1,0,3,2] row_mask:0xf bank_mask:0xf
	v_perm_b32 v137, v135, v133, v131
	v_perm_b32 v138, v136, v134, v131
	global_store_dword v130, v137, s[98:99] nt
	global_store_dword v130, v138, s[98:99] offset:256 nt
	v_max_f32_e32 v110, 0, v110
	v_max_f32_e32 v111, 0, v111
	v_max_f32_e32 v78, 0, v78
	v_max_f32_e32 v79, 0, v79
	v_pk_mul_f32 v[110:111], v[110:111], v[110:111]
	v_pk_mul_f32 v[78:79], v[78:79], v[78:79]
	v_cvt_pk_bf16_f32 v139, v110, v111
	v_cvt_pk_bf16_f32 v140, v78, v79
	s_add_u32 s98, s98, 0x4000
	s_addc_u32 s99, s99, 0
	v_mov_b32_dpp v141, v139 quad_perm:[1,0,3,2] row_mask:0xf bank_mask:0xf
	v_mov_b32_dpp v142, v140 quad_perm:[1,0,3,2] row_mask:0xf bank_mask:0xf
	v_perm_b32 v143, v141, v139, v131
	v_perm_b32 v144, v142, v140, v131
	global_store_dword v130, v143, s[98:99] nt
	global_store_dword v130, v144, s[98:99] offset:256 nt
	v_max_f32_e32 v48, 0, v48
	v_max_f32_e32 v49, 0, v49
	v_max_f32_e32 v16, 0, v16
	v_max_f32_e32 v17, 0, v17
	v_pk_mul_f32 v[48:49], v[48:49], v[48:49]
	v_pk_mul_f32 v[16:17], v[16:17], v[16:17]
	v_cvt_pk_bf16_f32 v133, v48, v49
	v_cvt_pk_bf16_f32 v134, v16, v17
	s_add_u32 s98, s98, 0x8c000
	s_addc_u32 s99, s99, 0
	v_mov_b32_dpp v135, v133 quad_perm:[1,0,3,2] row_mask:0xf bank_mask:0xf
	v_mov_b32_dpp v136, v134 quad_perm:[1,0,3,2] row_mask:0xf bank_mask:0xf
	v_perm_b32 v137, v135, v133, v131
	v_perm_b32 v138, v136, v134, v131
	global_store_dword v130, v137, s[98:99] nt
	global_store_dword v130, v138, s[98:99] offset:256 nt
	v_max_f32_e32 v50, 0, v50
; __device__ __forceinline__ bf16_t f2bf(float x) { return (bf16_t)(cvtpk(x, 0.f) & 0xffffu); }
; __device__ __forceinline__ int crow(int r, int hi) { return (r & 3) + 8 * (r >> 2) + 4 * hi; }
; template <class Epi>
; __device__ __forceinline__ void gemm8p(const bf16_t* __restrict__ A, int lda, const bf16_t* __restrict__ Bt, int ldb, int K,
;                                        LP lds, const Epi& epi, bool pre = false, const bf16_t* An = nullptr, const bf16_t* Bn = nullptr) {
;     ...
;   int e_rr = wr * 64, e_cc = wc * 32 + r32, e_hi = hi;
;   asm volatile("" : "+v"(e_rr), "+v"(e_cc), "+v"(e_hi));
; #pragma unroll
;   for (int a = 0; a < 2; ++a)
; #pragma unroll
;     for (int b = 0; b < 2; ++b)
; #pragma unroll
;       for (int m = 0; m < 2; ++m) { __builtin_amdgcn_sched_barrier(0); epi(a * 128 + e_rr + m * 32, b * 128 + e_cc, e_hi, acc[a][b][m]); }
; __device__ __forceinline__ void phase_gemm_w1(const Params& p, const bf16_t* __restrict__ WT, bool xonly, LP lds) {
;     ...
;     gemm8p(H + (size_t)row0 * 1024, 1024, WT + (size_t)col0 * 1024, 1024, 1024, lds, [&](int rr, int cc, int hi, f32x16 v) __attribute__((always_inline)) {
;       const int col = col0 + cc;
; #pragma unroll
;       for (int r = 0; r < 16; ++r) { const size_t row = row0 + rr + crow(r, hi); const float a = fmaxf(v[r], 0.f); __builtin_nontemporal_store(f2bf(a * a), U + row * 4096 + col); }
;     }, pre, hasn ? H + (size_t)rown * 1024 : nullptr, hasn ? WT + (size_t)coln * 1024 : nullptr);
	v_max_f32_e32 v51, 0, v51
	v_max_f32_e32 v18, 0, v18
	v_max_f32_e32 v19, 0, v19
	v_pk_mul_f32 v[50:51], v[50:51], v[50:51]
	v_pk_mul_f32 v[18:19], v[18:19], v[18:19]
	v_cvt_pk_bf16_f32 v139, v50, v51
	v_cvt_pk_bf16_f32 v140, v18, v19
	s_add_u32 s98, s98, 0x4000
	s_addc_u32 s99, s99, 0
	v_mov_b32_dpp v141, v139 quad_perm:[1,0,3,2] row_mask:0xf bank_mask:0xf
	v_mov_b32_dpp v142, v140 quad_perm:[1,0,3,2] row_mask:0xf bank_mask:0xf
	v_perm_b32 v143, v141, v139, v131
	v_perm_b32 v144, v142, v140, v131
	global_store_dword v130, v143, s[98:99] nt
	global_store_dword v130, v144, s[98:99] offset:256 nt
	v_max_f32_e32 v52, 0, v52
	v_max_f32_e32 v53, 0, v53
	v_max_f32_e32 v20, 0, v20
	v_max_f32_e32 v21, 0, v21
	v_pk_mul_f32 v[52:53], v[52:53], v[52:53]
	v_pk_mul_f32 v[20:21], v[20:21], v[20:21]
	v_cvt_pk_bf16_f32 v133, v52, v53
	v_cvt_pk_bf16_f32 v134, v20, v21
	s_add_u32 s98, s98, 0xc000
	s_addc_u32 s99, s99, 0
	v_mov_b32_dpp v135, v133 quad_perm:[1,0,3,2] row_mask:0xf bank_mask:0xf
	v_mov_b32_dpp v136, v134 quad_perm:[1,0,3,2] row_mask:0xf bank_mask:0xf
	v_perm_b32 v137, v135, v133, v131
	v_perm_b32 v138, v136, v134, v131
	global_store_dword v130, v137, s[98:99] nt
	global_store_dword v130, v138, s[98:99] offset:256 nt
	v_max_f32_e32 v54, 0, v54
	v_max_f32_e32 v55, 0, v55
	v_max_f32_e32 v22, 0, v22
	v_max_f32_e32 v23, 0, v23
	v_pk_mul_f32 v[54:55], v[54:55], v[54:55]
	v_pk_mul_f32 v[22:23], v[22:23], v[22:23]
	v_cvt_pk_bf16_f32 v139, v54, v55
	v_cvt_pk_bf16_f32 v140, v22, v23
	s_add_u32 s98, s98, 0x4000
	s_addc_u32 s99, s99, 0
	v_mov_b32_dpp v141, v139 quad_perm:[1,0,3,2] row_mask:0xf bank_mask:0xf
	v_mov_b32_dpp v142, v140 quad_perm:[1,0,3,2] row_mask:0xf bank_mask:0xf
	v_perm_b32 v143, v141, v139, v131
	v_perm_b32 v144, v142, v140, v131
	global_store_dword v130, v143, s[98:99] nt
	global_store_dword v130, v144, s[98:99] offset:256 nt
	v_max_f32_e32 v56, 0, v56
	v_max_f32_e32 v57, 0, v57
	v_max_f32_e32 v24, 0, v24
	v_max_f32_e32 v25, 0, v25
	v_pk_mul_f32 v[56:57], v[56:57], v[56:57]
	v_pk_mul_f32 v[24:25], v[24:25], v[24:25]
	v_cvt_pk_bf16_f32 v133, v56, v57
	v_cvt_pk_bf16_f32 v134, v24, v25
	s_add_u32 s98, s98, 0xc000
	s_addc_u32 s99, s99, 0
	v_mov_b32_dpp v135, v133 quad_perm:[1,0,3,2] row_mask:0xf bank_mask:0xf
	v_mov_b32_dpp v136, v134 quad_perm:[1,0,3,2] row_mask:0xf bank_mask:0xf
	v_perm_b32 v137, v135, v133, v131
	v_perm_b32 v138, v136, v134, v131
	global_store_dword v130, v137, s[98:99] nt
	global_store_dword v130, v138, s[98:99] offset:256 nt
	v_max_f32_e32 v58, 0, v58
	v_max_f32_e32 v59, 0, v59
	v_max_f32_e32 v26, 0, v26
	v_max_f32_e32 v27, 0, v27
	v_pk_mul_f32 v[58:59], v[58:59], v[58:59]
	v_pk_mul_f32 v[26:27], v[26:27], v[26:27]
	v_cvt_pk_bf16_f32 v139, v58, v59
	v_cvt_pk_bf16_f32 v140, v26, v27
	s_add_u32 s98, s98, 0x4000
	s_addc_u32 s99, s99, 0
	v_mov_b32_dpp v141, v139 quad_perm:[1,0,3,2] row_mask:0xf bank_mask:0xf
	v_mov_b32_dpp v142, v140 quad_perm:[1,0,3,2] row_mask:0xf bank_mask:0xf
	v_perm_b32 v143, v141, v139, v131
	v_perm_b32 v144, v142, v140, v131
	global_store_dword v130, v143, s[98:99] nt
	global_store_dword v130, v144, s[98:99] offset:256 nt
	v_max_f32_e32 v60, 0, v60
	v_max_f32_e32 v61, 0, v61
	v_max_f32_e32 v28, 0, v28
	v_max_f32_e32 v29, 0, v29
	v_pk_mul_f32 v[60:61], v[60:61], v[60:61]
	v_pk_mul_f32 v[28:29], v[28:29], v[28:29]
	v_cvt_pk_bf16_f32 v133, v60, v61
	v_cvt_pk_bf16_f32 v134, v28, v29
	s_add_u32 s98, s98, 0xc000
	s_addc_u32 s99, s99, 0
	v_mov_b32_dpp v135, v133 quad_perm:[1,0,3,2] row_mask:0xf bank_mask:0xf
	v_mov_b32_dpp v136, v134 quad_perm:[1,0,3,2] row_mask:0xf bank_mask:0xf
	v_perm_b32 v137, v135, v133, v131
	v_perm_b32 v138, v136, v134, v131
	global_store_dword v130, v137, s[98:99] nt
	global_store_dword v130, v138, s[98:99] offset:256 nt
	v_max_f32_e32 v62, 0, v62
	v_max_f32_e32 v63, 0, v63
	v_max_f32_e32 v30, 0, v30
	v_max_f32_e32 v31, 0, v31
	v_pk_mul_f32 v[62:63], v[62:63], v[62:63]
	v_pk_mul_f32 v[30:31], v[30:31], v[30:31]
	v_cvt_pk_bf16_f32 v139, v62, v63
	v_cvt_pk_bf16_f32 v140, v30, v31
	s_add_u32 s98, s98, 0x4000
	s_addc_u32 s99, s99, 0
	v_mov_b32_dpp v141, v139 quad_perm:[1,0,3,2] row_mask:0xf bank_mask:0xf
	v_mov_b32_dpp v142, v140 quad_perm:[1,0,3,2] row_mask:0xf bank_mask:0xf
	v_perm_b32 v143, v141, v139, v131
	v_perm_b32 v144, v142, v140, v131
	global_store_dword v130, v143, s[98:99] nt
	global_store_dword v130, v144, s[98:99] offset:256 nt
	v_max_f32_e32 v32, 0, v32
	v_max_f32_e32 v33, 0, v33
	v_max_f32_e32 v0, 0, v0
	v_max_f32_e32 v1, 0, v1
	v_pk_mul_f32 v[32:33], v[32:33], v[32:33]
	v_pk_mul_f32 v[0:1], v[0:1], v[0:1]
	v_cvt_pk_bf16_f32 v133, v32, v33
	v_cvt_pk_bf16_f32 v134, v0, v1
	s_add_u32 s98, s98, 0xc000
	s_addc_u32 s99, s99, 0
; __device__ __forceinline__ bf16_t f2bf(float x) { return (bf16_t)(cvtpk(x, 0.f) & 0xffffu); }
; __device__ __forceinline__ int crow(int r, int hi) { return (r & 3) + 8 * (r >> 2) + 4 * hi; }
; template <class Epi>
; __device__ __forceinline__ void gemm8p(const bf16_t* __restrict__ A, int lda, const bf16_t* __restrict__ Bt, int ldb, int K,
;                                        LP lds, const Epi& epi, bool pre = false, const bf16_t* An = nullptr, const bf16_t* Bn = nullptr) {
;     ...
;   int e_rr = wr * 64, e_cc = wc * 32 + r32, e_hi = hi;
;   asm volatile("" : "+v"(e_rr), "+v"(e_cc), "+v"(e_hi));
; #pragma unroll
;   for (int a = 0; a < 2; ++a)
; #pragma unroll
;     for (int b = 0; b < 2; ++b)
; #pragma unroll
;       for (int m = 0; m < 2; ++m) { __builtin_amdgcn_sched_barrier(0); epi(a * 128 + e_rr + m * 32, b * 128 + e_cc, e_hi, acc[a][b][m]); }
; __device__ __forceinline__ void phase_gemm_w1(const Params& p, const bf16_t* __restrict__ WT, bool xonly, LP lds) {
;     ...
;     gemm8p(H + (size_t)row0 * 1024, 1024, WT + (size_t)col0 * 1024, 1024, 1024, lds, [&](int rr, int cc, int hi, f32x16 v) __attribute__((always_inline)) {
;       const int col = col0 + cc;
; #pragma unroll
;       for (int r = 0; r < 16; ++r) { const size_t row = row0 + rr + crow(r, hi); const float a = fmaxf(v[r], 0.f); __builtin_nontemporal_store(f2bf(a * a), U + row * 4096 + col); }
;     }, pre, hasn ? H + (size_t)rown * 1024 : nullptr, hasn ? WT + (size_t)coln * 1024 : nullptr);
	v_mov_b32_dpp v135, v133 quad_perm:[1,0,3,2] row_mask:0xf bank_mask:0xf
	v_mov_b32_dpp v136, v134 quad_perm:[1,0,3,2] row_mask:0xf bank_mask:0xf
	v_perm_b32 v137, v135, v133, v131
	v_perm_b32 v138, v136, v134, v131
	global_store_dword v130, v137, s[98:99] nt
	global_store_dword v130, v138, s[98:99] offset:256 nt
	v_max_f32_e32 v34, 0, v34
	v_max_f32_e32 v35, 0, v35
	v_max_f32_e32 v2, 0, v2
	v_max_f32_e32 v3, 0, v3
	v_pk_mul_f32 v[34:35], v[34:35], v[34:35]
	v_pk_mul_f32 v[2:3], v[2:3], v[2:3]
	v_cvt_pk_bf16_f32 v139, v34, v35
	v_cvt_pk_bf16_f32 v140, v2, v3
	s_add_u32 s98, s98, 0x4000
	s_addc_u32 s99, s99, 0
	v_mov_b32_dpp v141, v139 quad_perm:[1,0,3,2] row_mask:0xf bank_mask:0xf
	v_mov_b32_dpp v142, v140 quad_perm:[1,0,3,2] row_mask:0xf bank_mask:0xf
	v_perm_b32 v143, v141, v139, v131
	v_perm_b32 v144, v142, v140, v131
	global_store_dword v130, v143, s[98:99] nt
	global_store_dword v130, v144, s[98:99] offset:256 nt
	v_max_f32_e32 v36, 0, v36
	v_max_f32_e32 v37, 0, v37
	v_max_f32_e32 v4, 0, v4
	v_max_f32_e32 v5, 0, v5
	v_pk_mul_f32 v[36:37], v[36:37], v[36:37]
	v_pk_mul_f32 v[4:5], v[4:5], v[4:5]
	v_cvt_pk_bf16_f32 v133, v36, v37
	v_cvt_pk_bf16_f32 v134, v4, v5
	s_add_u32 s98, s98, 0xc000
	s_addc_u32 s99, s99, 0
	v_mov_b32_dpp v135, v133 quad_perm:[1,0,3,2] row_mask:0xf bank_mask:0xf
	v_mov_b32_dpp v136, v134 quad_perm:[1,0,3,2] row_mask:0xf bank_mask:0xf
	v_perm_b32 v137, v135, v133, v131
	v_perm_b32 v138, v136, v134, v131
	global_store_dword v130, v137, s[98:99] nt
	global_store_dword v130, v138, s[98:99] offset:256 nt
	v_max_f32_e32 v38, 0, v38
	v_max_f32_e32 v39, 0, v39
	v_max_f32_e32 v6, 0, v6
	v_max_f32_e32 v7, 0, v7
	v_pk_mul_f32 v[38:39], v[38:39], v[38:39]
	v_pk_mul_f32 v[6:7], v[6:7], v[6:7]
	v_cvt_pk_bf16_f32 v139, v38, v39
	v_cvt_pk_bf16_f32 v140, v6, v7
	s_add_u32 s98, s98, 0x4000
	s_addc_u32 s99, s99, 0
	v_mov_b32_dpp v141, v139 quad_perm:[1,0,3,2] row_mask:0xf bank_mask:0xf
	v_mov_b32_dpp v142, v140 quad_perm:[1,0,3,2] row_mask:0xf bank_mask:0xf
	v_perm_b32 v143, v141, v139, v131
	v_perm_b32 v144, v142, v140, v131
	global_store_dword v130, v143, s[98:99] nt
	global_store_dword v130, v144, s[98:99] offset:256 nt
	v_max_f32_e32 v40, 0, v40
	v_max_f32_e32 v41, 0, v41
	v_max_f32_e32 v8, 0, v8
	v_max_f32_e32 v9, 0, v9
	v_pk_mul_f32 v[40:41], v[40:41], v[40:41]
	v_pk_mul_f32 v[8:9], v[8:9], v[8:9]
	v_cvt_pk_bf16_f32 v133, v40, v41
	v_cvt_pk_bf16_f32 v134, v8, v9
	s_add_u32 s98, s98, 0xc000
	s_addc_u32 s99, s99, 0
	v_mov_b32_dpp v135, v133 quad_perm:[1,0,3,2] row_mask:0xf bank_mask:0xf
	v_mov_b32_dpp v136, v134 quad_perm:[1,0,3,2] row_mask:0xf bank_mask:0xf
	v_perm_b32 v137, v135, v133, v131
	v_perm_b32 v138, v136, v134, v131
	global_store_dword v130, v137, s[98:99] nt
	global_store_dword v130, v138, s[98:99] offset:256 nt
	v_max_f32_e32 v42, 0, v42
	v_max_f32_e32 v43, 0, v43
	v_max_f32_e32 v10, 0, v10
	v_max_f32_e32 v11, 0, v11
	v_pk_mul_f32 v[42:43], v[42:43], v[42:43]
	v_pk_mul_f32 v[10:11], v[10:11], v[10:11]
	v_cvt_pk_bf16_f32 v139, v42, v43
	v_cvt_pk_bf16_f32 v140, v10, v11
	s_add_u32 s98, s98, 0x4000
	s_addc_u32 s99, s99, 0
	v_mov_b32_dpp v141, v139 quad_perm:[1,0,3,2] row_mask:0xf bank_mask:0xf
	v_mov_b32_dpp v142, v140 quad_perm:[1,0,3,2] row_mask:0xf bank_mask:0xf
	v_perm_b32 v143, v141, v139, v131
	v_perm_b32 v144, v142, v140, v131
	global_store_dword v130, v143, s[98:99] nt
	global_store_dword v130, v144, s[98:99] offset:256 nt
	v_max_f32_e32 v44, 0, v44
	v_max_f32_e32 v45, 0, v45
	v_max_f32_e32 v12, 0, v12
	v_max_f32_e32 v13, 0, v13
	v_pk_mul_f32 v[44:45], v[44:45], v[44:45]
	v_pk_mul_f32 v[12:13], v[12:13], v[12:13]
	v_cvt_pk_bf16_f32 v133, v44, v45
	v_cvt_pk_bf16_f32 v134, v12, v13
	s_add_u32 s98, s98, 0xc000
	s_addc_u32 s99, s99, 0
	v_mov_b32_dpp v135, v133 quad_perm:[1,0,3,2] row_mask:0xf bank_mask:0xf
	v_mov_b32_dpp v136, v134 quad_perm:[1,0,3,2] row_mask:0xf bank_mask:0xf
	v_perm_b32 v137, v135, v133, v131
	v_perm_b32 v138, v136, v134, v131
	global_store_dword v130, v137, s[98:99] nt
	global_store_dword v130, v138, s[98:99] offset:256 nt
	v_max_f32_e32 v46, 0, v46
	v_max_f32_e32 v47, 0, v47
	v_max_f32_e32 v14, 0, v14
	v_max_f32_e32 v15, 0, v15
	v_pk_mul_f32 v[46:47], v[46:47], v[46:47]
	v_pk_mul_f32 v[14:15], v[14:15], v[14:15]
	v_cvt_pk_bf16_f32 v139, v46, v47
	v_cvt_pk_bf16_f32 v140, v14, v15
	s_add_u32 s98, s98, 0x4000
	s_addc_u32 s99, s99, 0
	v_mov_b32_dpp v141, v139 quad_perm:[1,0,3,2] row_mask:0xf bank_mask:0xf
	v_mov_b32_dpp v142, v140 quad_perm:[1,0,3,2] row_mask:0xf bank_mask:0xf
	v_perm_b32 v143, v141, v139, v131
	v_perm_b32 v144, v142, v140, v131
	global_store_dword v130, v143, s[98:99] nt
	global_store_dword v130, v144, s[98:99] offset:256 nt

; __global__ void __launch_bounds__(NTHREADS) fwd_kernel(Params p) {
;   extern __shared__ __attribute__((aligned(16))) char lds_raw[];
	.amdhsa_kernel _Z10fwd_kernel6Params
		.amdhsa_group_segment_fixed_size 0
		.amdhsa_private_segment_fixed_size 0
		.amdhsa_kernarg_size 512
		.amdhsa_user_sgpr_count 2
		.amdhsa_user_sgpr_dispatch_ptr 0
		.amdhsa_user_sgpr_queue_ptr 0
		.amdhsa_user_sgpr_kernarg_segment_ptr 1
		.amdhsa_user_sgpr_dispatch_id 0
		.amdhsa_user_sgpr_kernarg_preload_length 0
		.amdhsa_user_sgpr_kernarg_preload_offset 0
		.amdhsa_user_sgpr_private_segment_size 0
		.amdhsa_uses_dynamic_stack 0
		.amdhsa_enable_private_segment 0
		.amdhsa_system_sgpr_workgroup_id_x 1
		.amdhsa_system_sgpr_workgroup_id_y 0
		.amdhsa_system_sgpr_workgroup_id_z 0
		.amdhsa_system_sgpr_workgroup_info 0
		.amdhsa_system_vgpr_workitem_id 2
		.amdhsa_next_free_vgpr 256
		.amdhsa_next_free_sgpr 102
		.amdhsa_accum_offset 256
		.amdhsa_reserve_vcc 1
		.amdhsa_float_round_mode_32 0
		.amdhsa_float_round_mode_16_64 0
		.amdhsa_float_denorm_mode_32 3
		.amdhsa_float_denorm_mode_16_64 3
		.amdhsa_dx10_clamp 1
		.amdhsa_ieee_mode 1
		.amdhsa_fp16_overflow 0
		.amdhsa_tg_split 0
		.amdhsa_exception_fp_ieee_invalid_op 0
		.amdhsa_exception_fp_denorm_src 0
		.amdhsa_exception_fp_ieee_div_zero 0
		.amdhsa_exception_fp_ieee_overflow 0
		.amdhsa_exception_fp_ieee_underflow 0
		.amdhsa_exception_fp_ieee_inexact 0
		.amdhsa_exception_int_div_zero 0
	.end_amdhsa_kernel

; __global__ void __launch_bounds__(NTHREADS) fwd_kernel(Params p) {
;   extern __shared__ __attribute__((aligned(16))) char lds_raw[];
amdhsa.kernels:
  - .agpr_count:     0
    .args:
      - .offset:         0
        .size:           256
        .value_kind:     by_value
      - .offset:         256
        .size:           4
        .value_kind:     hidden_block_count_x
      - .offset:         260
        .size:           4
        .value_kind:     hidden_block_count_y
      - .offset:         264
        .size:           4
        .value_kind:     hidden_block_count_z
      - .offset:         268
        .size:           2
        .value_kind:     hidden_group_size_x
      - .offset:         270
        .size:           2
        .value_kind:     hidden_group_size_y
      - .offset:         272
        .size:           2
        .value_kind:     hidden_group_size_z
      - .offset:         274
        .size:           2
        .value_kind:     hidden_remainder_x
      - .offset:         276
        .size:           2
        .value_kind:     hidden_remainder_y
      - .offset:         278
        .size:           2
        .value_kind:     hidden_remainder_z
      - .offset:         296
        .size:           8
        .value_kind:     hidden_global_offset_x
      - .offset:         304
        .size:           8
        .value_kind:     hidden_global_offset_y
      - .offset:         312
        .size:           8
        .value_kind:     hidden_global_offset_z
      - .offset:         320
        .size:           2
        .value_kind:     hidden_grid_dims
      - .offset:         344
        .size:           8
        .value_kind:     hidden_multigrid_sync_arg
      - .offset:         376
        .size:           4
        .value_kind:     hidden_dynamic_lds_size
    .group_segment_fixed_size: 0
    .kernarg_segment_align: 8
    .kernarg_segment_size: 512
    .language:       OpenCL C
    .language_version:
      - 2
      - 0
    .max_flat_workgroup_size: 512
    .name:           _Z10fwd_kernel6Params
    .private_segment_fixed_size: 0
    .sgpr_count:     108
    .sgpr_spill_count: 86
    .symbol:         _Z10fwd_kernel6Params.kd
    .uniform_work_group_size: 1
    .uses_dynamic_stack: false
    .vgpr_count:     256
    .vgpr_spill_count: 0
    .wavefront_size: 64
